# stack10 plus batched census counter loads at the first grid barrier (ksc batching dropped)
# speedup vs baseline: 1.0173x; 1.0078x over previous
; __device__ __forceinline__ unsigned xb_ld(unsigned* p)              { return __hip_atomic_load(p, __ATOMIC_RELAXED, __HIP_MEMORY_SCOPE_AGENT); }
; __device__ __forceinline__ void xcd_barrier_complete(unsigned* bar, unsigned x, unsigned& nloc, unsigned& nx) {
;     ...
;     for (;;) {
;         sum = 0u; cnt = 0u; mine = 0u;
; #pragma unroll
;         for (unsigned j = 0; j < 16; ++j) { const unsigned c = xb_ld(&bar[XB_XCNT(j)]); sum += c; cnt += (c > 0u) ? 1u : 0u; mine = (j == x) ? c : mine; }
;         if (sum == G) break;
.LBB0_126:
	v_readlane_b32 s4, v251, 53
	v_readlane_b32 s5, v251, 54
	s_mov_b64 s[6:7], -1
	s_nop 3
	global_load_dword v0, v1, s[4:5] sc1
	v_readlane_b32 s4, v251, 55
	v_readlane_b32 s5, v251, 56
	s_waitcnt lgkmcnt(0)
	s_nop 3
	global_load_dword v2, v1, s[4:5] sc1
	v_readlane_b32 s4, v251, 57
	v_readlane_b32 s5, v251, 58
	s_nop 4
	global_load_dword v3, v1, s[4:5] sc1
	v_readlane_b32 s4, v251, 59
	v_readlane_b32 s5, v251, 60
	s_nop 4
	global_load_dword v4, v1, s[4:5] sc1
	v_readlane_b32 s4, v251, 61
	v_readlane_b32 s5, v251, 62
	s_nop 4
	global_load_dword v5, v1, s[4:5] sc1
	v_readlane_b32 s4, v251, 63
	v_readlane_b32 s5, v252, 0
	s_nop 4
	global_load_dword v6, v1, s[4:5] sc1
	v_readlane_b32 s4, v252, 1
	v_readlane_b32 s5, v252, 2
	s_nop 4
	global_load_dword v7, v1, s[4:5] sc1
	v_readlane_b32 s4, v252, 3
	v_readlane_b32 s5, v252, 4
	s_nop 4
	global_load_dword v8, v1, s[4:5] sc1
	v_readlane_b32 s4, v252, 5
	v_readlane_b32 s5, v252, 6
	s_nop 4
	global_load_dword v9, v1, s[4:5] sc1
	v_readlane_b32 s4, v252, 7
	v_readlane_b32 s5, v252, 8
	s_nop 4
	global_load_dword v10, v1, s[4:5] sc1
	v_readlane_b32 s4, v252, 9
	v_readlane_b32 s5, v252, 10
	s_nop 4
	global_load_dword v11, v1, s[4:5] sc1
	v_readlane_b32 s4, v252, 11
	v_readlane_b32 s5, v252, 12
	s_nop 4
	global_load_dword v12, v1, s[4:5] sc1
	v_readlane_b32 s4, v252, 13
	v_readlane_b32 s5, v252, 14
	s_nop 4
	global_load_dword v13, v1, s[4:5] sc1
	v_readlane_b32 s4, v252, 15
	v_readlane_b32 s5, v252, 16
	s_nop 4
	global_load_dword v14, v1, s[4:5] sc1
	v_readlane_b32 s4, v252, 17
	v_readlane_b32 s5, v252, 18
	s_nop 4
	global_load_dword v15, v1, s[4:5] sc1
	v_readlane_b32 s4, v252, 19
	v_readlane_b32 s5, v252, 20
	s_nop 4
	global_load_dword v16, v1, s[4:5] sc1
	s_mov_b64 s[4:5], -1
	s_waitcnt vmcnt(0)
	v_add_u32_e32 v17, v2, v0
	v_add_u32_e32 v17, v17, v3
	v_add_u32_e32 v17, v17, v4
	v_add_u32_e32 v17, v17, v5
	v_add_u32_e32 v17, v17, v6
	v_add_u32_e32 v17, v17, v7
	v_add_u32_e32 v17, v17, v8
	v_add_u32_e32 v17, v17, v9
	v_add_u32_e32 v17, v17, v10
	v_add_u32_e32 v17, v17, v11
	v_add_u32_e32 v17, v17, v12
	v_add_u32_e32 v17, v17, v13
	v_add_u32_e32 v17, v17, v14
	v_add_u32_e32 v17, v17, v15
	v_add_u32_e32 v17, v17, v16
	v_cmp_eq_u32_e32 vcc, s36, v17
	s_cbranch_vccnz .LBB0_125
	s_and_b32 s3, s2, 0xff
	s_cmp_eq_u32 s3, 0
	s_mov_b64 s[8:9], -1
	s_sleep 1
	s_cbranch_scc1 .LBB0_130
	s_and_b64 vcc, exec, s[8:9]
	s_cbranch_vccz .LBB0_125
